# no setprio + attention next-unit ticket: wait for the atomic moved from unit start to unit end
# baseline (speedup 1.0000x reference)
.LBB0_771:
	s_lshr_b32 s44, s40, 8
	v_mov_b32_e32 v223, 0
	s_and_saveexec_b64 s[4:5], s[0:1]
	s_cbranch_execz .LBB0_775
	s_mov_b64 s[8:9], exec
	v_mbcnt_lo_u32_b32 v0, s8, 0
	v_mbcnt_hi_u32_b32 v0, s9, v0
	v_cmp_eq_u32_e32 vcc, 0, v0
	s_and_saveexec_b64 s[6:7], vcc
	s_cbranch_execz .LBB0_774
	s_lshl_b32 s2, s44, 8
	s_bcnt1_i32_b64 s8, s[8:9]
	v_mov_b32_e32 v2, s2
	v_mov_b32_e32 v3, s8
	global_atomic_add v252, v2, v3, s[82:83] sc0
.LBB0_774:
	s_or_b64 exec, exec, s[6:7]
.LBB0_775:
	s_or_b64 exec, exec, s[4:5]
	s_lshr_b32 s2, s40, 4
	s_and_b32 s2, s2, 12
	s_and_b32 s4, s40, 3
	s_or_b32 s2, s2, s4
	s_lshl_b32 s26, s2, 3
	s_add_i32 s26, s26, s44
	s_lshr_b32 s2, s26, 1
	s_and_b32 s2, s2, 6
	s_bfe_u32 s4, s40, 0x10008
	v_mov_b32_e32 v4, v236
	s_bfe_u32 s30, s40, 0x40002
	s_or_b32 s8, s2, s4
	s_lshl_b32 s4, s26, 8
	v_readfirstlane_b32 s9, v4
	s_ashr_i32 s2, s9, 6
	s_and_b32 s10, s4, 0xfffff000
	s_lshl_b32 s4, s30, 8
	s_xor_b32 s27, s4, 0xf00
	s_lshl_b32 s31, s2, 5
	s_or_b32 s4, s10, s27
	s_ashr_i32 s5, s31, 31
	s_add_u32 s4, s31, s4
	s_addc_u32 s5, s5, 0
	s_lshl_b64 s[6:7], s[4:5], 10
	s_add_u32 s6, s92, s6
	s_addc_u32 s7, s93, s7
	s_lshl_b32 s24, s26, 6
	s_and_b32 s28, s24, 0x380
	s_add_u32 s6, s6, s28
	s_addc_u32 s7, s7, 0
	s_lshl_b64 s[24:25], s[10:11], 10
	s_add_u32 s10, s36, s24
	s_addc_u32 s29, s37, s25
	s_add_u32 s28, s10, s28
	s_addc_u32 s29, s29, 0
	s_add_u32 s10, s34, s24
	v_and_b32_e32 v224, 63, v4
	s_addc_u32 s25, s35, s25
	s_lshl_b32 s8, s8, 7
	s_add_u32 s24, s10, s8
	v_lshlrev_b32_e32 v0, 10, v224
	s_addc_u32 s25, s25, 0
	v_lshl_add_u64 v[2:3], s[28:29], 0, v[0:1]
	s_lshl_b32 s8, s2, 4
	v_bfe_u32 v0, v4, 2, 4
	s_lshl_b32 s28, s2, 3
	v_and_or_b32 v0, s8, 48, v0
	s_ashr_i32 s29, s28, 31
	v_lshlrev_b32_e32 v0, 10, v0
	s_ashr_i32 s8, s9, 3
	v_lshl_add_u64 v[212:213], s[28:29], 1, v[2:3]
	v_lshl_add_u64 v[2:3], s[24:25], 0, v[0:1]
	s_and_b32 s24, s8, 0xffffffe0
	s_ashr_i32 s25, s24, 31
	s_lshl_b32 s8, s2, 10
	v_lshlrev_b32_e32 v225, 3, v4
	s_cmp_lg_u32 0, -1
	v_and_b32_e32 v228, 24, v225
	s_cselect_b32 s10, 0, 0
	v_and_b32_e32 v226, 31, v4
	v_lshl_add_u64 v[2:3], s[24:25], 1, v[2:3]
	v_lshlrev_b32_e32 v0, 1, v228
	s_add_i32 s45, s8, s10
	s_mov_b32 s10, m0
	s_mov_b32 m0, s45
	s_nop 0
	global_load_lds_dwordx4 v[212:213], off
	s_mov_b32 m0, s10
	v_bfe_u32 v227, v4, 5, 1
	v_lshl_add_u64 v[2:3], v[2:3], 0, v[0:1]
	s_add_i32 s46, s45, 0x6000
	s_mov_b32 s10, m0
	s_mov_b32 m0, s46
	s_nop 0
	global_load_lds_dwordx4 v[2:3], off
	s_mov_b32 m0, s10
	v_lshlrev_b32_e32 v0, 10, v226
	v_lshl_add_u64 v[6:7], v[212:213], 0, s[12:13]
	s_add_i32 s10, s45, 0x2000
	s_mov_b32 s24, m0
	s_mov_b32 m0, s10
	s_nop 0
	global_load_lds_dwordx4 v[6:7], off
	s_mov_b32 m0, s24
	v_lshl_or_b32 v0, v227, 4, v0
	global_load_dwordx4 v[164:167], v0, s[6:7]
	global_load_dwordx4 v[156:159], v0, s[6:7] offset:32
	global_load_dwordx4 v[148:151], v0, s[6:7] offset:64
	global_load_dwordx4 v[144:147], v0, s[6:7] offset:96
	v_mov_b64_e32 v[46:47], v[30:31]
	v_mov_b64_e32 v[44:45], v[28:29]
	v_mov_b64_e32 v[42:43], v[26:27]
	v_mov_b64_e32 v[40:41], v[24:25]
	v_mov_b64_e32 v[38:39], v[22:23]
	v_mov_b64_e32 v[36:37], v[20:21]
	v_mov_b64_e32 v[34:35], v[18:19]
	v_mov_b64_e32 v[32:33], v[16:17]
	v_lshlrev_b32_e32 v0, 10, v227
	v_lshlrev_b32_e32 v5, 4, v226
	v_lshl_add_u64 v[6:7], v[212:213], 0, s[14:15]
	s_add_i32 s6, s45, 0x4000
	s_mov_b32 s7, m0
	s_mov_b32 m0, s6
	s_nop 0
	global_load_lds_dwordx4 v[6:7], off
	s_mov_b32 m0, s7
	v_add3_u32 v235, 0, v0, v5
	s_waitcnt vmcnt(3) lgkmcnt(0)
	s_barrier
	ds_read_b128 v[6:9], v235
	s_cmp_lg_u32 s30, 15
	s_cselect_b64 s[6:7], -1, 0
	v_lshlrev_b32_e32 v230, 2, v227
	v_or_b32_e32 v233, s31, v226
	s_and_b64 vcc, exec, s[6:7]
	s_waitcnt vmcnt(3) lgkmcnt(0)
	v_mfma_f32_32x32x16_bf16 v[48:63], v[6:9], v[164:167], v[32:47]
	ds_read_b128 v[6:9], v235 offset:512
	s_waitcnt lgkmcnt(0)
	v_mfma_f32_32x32x16_bf16 v[32:47], v[6:9], v[164:167], v[32:47]
	ds_read_b128 v[6:9], v235 offset:2048
	s_waitcnt vmcnt(2) lgkmcnt(0)
	v_mfma_f32_32x32x16_bf16 v[48:63], v[6:9], v[156:159], v[48:63]
	ds_read_b128 v[6:9], v235 offset:2560
	s_waitcnt lgkmcnt(0)
	v_mfma_f32_32x32x16_bf16 v[32:47], v[6:9], v[156:159], v[32:47]
	ds_read_b128 v[6:9], v235 offset:4096
	s_waitcnt vmcnt(1) lgkmcnt(0)
	v_mfma_f32_32x32x16_bf16 v[48:63], v[6:9], v[148:151], v[48:63]
	ds_read_b128 v[6:9], v235 offset:4608
	s_waitcnt lgkmcnt(0)
	v_mfma_f32_32x32x16_bf16 v[32:47], v[6:9], v[148:151], v[32:47]
	ds_read_b128 v[6:9], v235 offset:6144
	s_waitcnt vmcnt(0) lgkmcnt(0)
	v_mfma_f32_32x32x16_bf16 v[48:63], v[6:9], v[144:147], v[48:63]
	ds_read_b128 v[6:9], v235 offset:6656
	s_waitcnt lgkmcnt(0)
	v_mfma_f32_32x32x16_bf16 v[32:47], v[6:9], v[144:147], v[32:47]
	s_nop 15
	s_nop 7
	s_cbranch_vccnz .LBB0_777
	v_or_b32_e32 v0, 32, v230
	v_cmp_le_i32_e32 vcc, v0, v233
	v_or_b32_e32 v0, 33, v230
	s_nop 7
	v_cndmask_b32_e32 v32, v222, v32, vcc
	v_cmp_lt_i32_e32 vcc, v230, v233
	s_nop 1
	v_cndmask_b32_e32 v49, v222, v49, vcc
	v_cmp_le_i32_e32 vcc, v230, v233
	s_nop 1
	v_cndmask_b32_e32 v48, v222, v48, vcc
	v_cmp_le_i32_e32 vcc, v0, v233
	v_or_b32_e32 v0, 2, v230
	s_nop 0
	v_cndmask_b32_e32 v33, v222, v33, vcc
	v_cmp_le_i32_e32 vcc, v0, v233
	v_or_b32_e32 v0, 34, v230
	s_nop 0
	v_cndmask_b32_e32 v50, v222, v50, vcc
	v_cmp_le_i32_e32 vcc, v0, v233
	v_or_b32_e32 v0, 3, v230
	s_nop 0
	v_cndmask_b32_e32 v34, v222, v34, vcc
	v_cmp_le_i32_e32 vcc, v0, v233
	v_or_b32_e32 v0, 35, v230
	s_nop 0
	v_cndmask_b32_e32 v51, v222, v51, vcc
	v_cmp_le_i32_e32 vcc, v0, v233
	v_or_b32_e32 v0, 8, v230
	s_nop 0
	v_cndmask_b32_e32 v35, v222, v35, vcc
	v_cmp_le_i32_e32 vcc, v0, v233
	v_or_b32_e32 v0, 40, v230
	s_nop 0
	v_cndmask_b32_e32 v52, v222, v52, vcc
	v_cmp_le_i32_e32 vcc, v0, v233
	v_or_b32_e32 v0, 9, v230
	s_nop 0
	v_cndmask_b32_e32 v36, v222, v36, vcc
	v_cmp_le_i32_e32 vcc, v0, v233
	v_or_b32_e32 v0, 41, v230
	s_nop 0
	v_cndmask_b32_e32 v53, v222, v53, vcc
	v_cmp_le_i32_e32 vcc, v0, v233
	v_or_b32_e32 v0, 10, v230
	s_nop 0
	v_cndmask_b32_e32 v37, v222, v37, vcc
	v_cmp_le_i32_e32 vcc, v0, v233
	v_or_b32_e32 v0, 42, v230
	s_nop 0
	v_cndmask_b32_e32 v54, v222, v54, vcc
	v_cmp_le_i32_e32 vcc, v0, v233
	v_or_b32_e32 v0, 11, v230
	s_nop 0
	v_cndmask_b32_e32 v38, v222, v38, vcc
	v_cmp_le_i32_e32 vcc, v0, v233
	v_or_b32_e32 v0, 43, v230
	s_nop 0
	v_cndmask_b32_e32 v55, v222, v55, vcc
	v_cmp_le_i32_e32 vcc, v0, v233
	v_or_b32_e32 v0, 16, v230
	s_nop 0
	v_cndmask_b32_e32 v39, v222, v39, vcc
	v_cmp_le_i32_e32 vcc, v0, v233
	v_or_b32_e32 v0, 48, v230
	s_nop 0
	v_cndmask_b32_e32 v56, v222, v56, vcc
	v_cmp_le_i32_e32 vcc, v0, v233
	v_or_b32_e32 v0, 17, v230
	s_nop 0
	v_cndmask_b32_e32 v40, v222, v40, vcc
	v_cmp_le_i32_e32 vcc, v0, v233
	v_or_b32_e32 v0, 49, v230
	s_nop 0
	v_cndmask_b32_e32 v57, v222, v57, vcc
	v_cmp_le_i32_e32 vcc, v0, v233
	v_or_b32_e32 v0, 18, v230
	s_nop 0
	v_cndmask_b32_e32 v41, v222, v41, vcc
	v_cmp_le_i32_e32 vcc, v0, v233
	v_or_b32_e32 v0, 50, v230
	s_nop 0
	v_cndmask_b32_e32 v58, v222, v58, vcc
	v_cmp_le_i32_e32 vcc, v0, v233
	v_or_b32_e32 v0, 19, v230
	s_nop 0
	v_cndmask_b32_e32 v42, v222, v42, vcc
	v_cmp_le_i32_e32 vcc, v0, v233
	v_or_b32_e32 v0, 51, v230
	s_nop 0
	v_cndmask_b32_e32 v59, v222, v59, vcc
	v_cmp_le_i32_e32 vcc, v0, v233
	v_or_b32_e32 v0, 24, v230
	s_nop 0
	v_cndmask_b32_e32 v43, v222, v43, vcc
	v_cmp_le_i32_e32 vcc, v0, v233
	v_or_b32_e32 v0, 56, v230
	s_nop 0
	v_cndmask_b32_e32 v60, v222, v60, vcc
	v_cmp_le_i32_e32 vcc, v0, v233
	v_or_b32_e32 v0, 25, v230
	s_nop 0
	v_cndmask_b32_e32 v44, v222, v44, vcc
	v_cmp_le_i32_e32 vcc, v0, v233
	v_or_b32_e32 v0, 57, v230
	s_nop 0
	v_cndmask_b32_e32 v61, v222, v61, vcc
	v_cmp_le_i32_e32 vcc, v0, v233
	v_or_b32_e32 v0, 26, v230
	s_nop 0
	v_cndmask_b32_e32 v45, v222, v45, vcc
	v_cmp_le_i32_e32 vcc, v0, v233
	v_or_b32_e32 v0, 58, v230
	s_nop 0
	v_cndmask_b32_e32 v62, v222, v62, vcc
	v_cmp_le_i32_e32 vcc, v0, v233
	v_or_b32_e32 v0, 27, v230
	s_nop 0
	v_cndmask_b32_e32 v46, v222, v46, vcc
	v_cmp_le_i32_e32 vcc, v0, v233
	v_or_b32_e32 v0, 59, v230
	s_nop 0
	v_cndmask_b32_e32 v63, v222, v63, vcc
	v_cmp_le_i32_e32 vcc, v0, v233
	s_nop 1
	v_cndmask_b32_e32 v47, v222, v47, vcc

.LBB0_798:
	v_add_f32_e32 v4, v80, v81
	v_add_f32_e32 v4, v82, v4
	v_add_f32_e32 v4, v83, v4
	v_add_f32_e32 v4, v84, v4
	v_add_f32_e32 v4, v85, v4
	v_add_f32_e32 v4, v86, v4
	v_add_f32_e32 v4, v87, v4
	v_add_f32_e32 v4, v88, v4
	v_add_f32_e32 v4, v89, v4
	v_add_f32_e32 v4, v90, v4
	v_add_f32_e32 v4, v91, v4
	v_add_f32_e32 v4, v92, v4
	v_add_f32_e32 v4, v93, v4
	v_add_f32_e32 v4, v94, v4
	v_add_f32_e32 v4, v95, v4
	v_add_f32_e32 v4, v64, v4
	v_add_f32_e32 v4, v65, v4
	v_add_f32_e32 v4, v66, v4
	v_add_f32_e32 v4, v67, v4
	v_add_f32_e32 v4, v68, v4
	v_add_f32_e32 v4, v69, v4
	v_add_f32_e32 v4, v70, v4
	v_add_f32_e32 v4, v71, v4
	v_add_f32_e32 v4, v72, v4
	v_add_f32_e32 v4, v73, v4
	v_add_f32_e32 v4, v74, v4
	v_add_f32_e32 v4, v75, v4
	v_add_f32_e32 v4, v76, v4
	s_cmp_lg_u32 0, -1
	v_add_f32_e32 v4, v77, v4
	s_cselect_b32 s6, 0, 0
	v_add_f32_e32 v4, v78, v4
	s_addk_i32 s6, 0x6000
	v_add_f32_e32 v4, v79, v4
	v_add3_u32 v3, v231, s6, v228
	v_add_f32_e32 v0, v0, v4
	v_cvt_pk_bf16_f32 v4, v80, v81
	v_cvt_pk_bf16_f32 v5, v82, v83
	v_cvt_pk_bf16_f32 v6, v84, v85
	v_cvt_pk_bf16_f32 v7, v86, v87
	v_cvt_pk_bf16_f32 v8, v88, v89
	v_cvt_pk_bf16_f32 v9, v90, v91
	v_cvt_pk_bf16_f32 v10, v92, v93
	v_cvt_pk_bf16_f32 v11, v94, v95
	v_cvt_pk_bf16_f32 v12, v64, v65
	v_cvt_pk_bf16_f32 v13, v66, v67
	v_cvt_pk_bf16_f32 v14, v68, v69
	v_cvt_pk_bf16_f32 v15, v70, v71
	v_cvt_pk_bf16_f32 v64, v72, v73
	v_cvt_pk_bf16_f32 v65, v74, v75
	v_cvt_pk_bf16_f32 v66, v76, v77
	v_cvt_pk_bf16_f32 v67, v78, v79
	v_add3_u32 v3, v3, v229, s48
	ds_read_b64_tr_b16 v[68:69],v3 offset:0
	ds_read_b64_tr_b16 v[70:71],v3 offset:512
	ds_read_b64_tr_b16 v[72:73],v3 offset:1024
	ds_read_b64_tr_b16 v[74:75],v3 offset:1536
	ds_read_b64_tr_b16 v[76:77],v3 offset:2048
	ds_read_b64_tr_b16 v[78:79],v3 offset:2560
	ds_read_b64_tr_b16 v[80:81],v3 offset:3072
	ds_read_b64_tr_b16 v[82:83],v3 offset:3584
	s_waitcnt lgkmcnt(0)
	s_nop 0
	v_mfma_f32_32x32x16_bf16 v[48:63], v[4:7], v[68:71], v[48:63]
	ds_read_b64_tr_b16 v[68:69],v3 offset:4096
	ds_read_b64_tr_b16 v[70:71],v3 offset:4608
	v_mfma_f32_32x32x16_bf16 v[48:63], v[8:11], v[72:75], v[48:63]
	ds_read_b64_tr_b16 v[72:73],v3 offset:5120
	ds_read_b64_tr_b16 v[74:75],v3 offset:5632
	v_mfma_f32_32x32x16_bf16 v[48:63], v[12:15], v[76:79], v[48:63]
	ds_read_b64_tr_b16 v[76:77],v3 offset:6144
	ds_read_b64_tr_b16 v[78:79],v3 offset:6656
	ds_read_b64_tr_b16 v[84:85],v3 offset:7168
	ds_read_b64_tr_b16 v[86:87],v3 offset:7680
	s_waitcnt lgkmcnt(0)
	v_mfma_f32_32x32x16_bf16 v[48:63], v[64:67], v[80:83], v[48:63]
	v_mfma_f32_32x32x16_bf16 v[32:47], v[4:7], v[68:71], v[32:47]
	v_mov_b32_e32 v3, v0
	s_nop 1
	v_permlane32_swap_b32_e32 v0, v3
	v_cmp_gt_u32_e32 vcc, 32, v224
	v_mfma_f32_32x32x16_bf16 v[32:47], v[8:11], v[72:75], v[32:47]
	v_mfma_f32_32x32x16_bf16 v[32:47], v[12:15], v[76:79], v[32:47]
	v_mfma_f32_32x32x16_bf16 v[32:47], v[64:67], v[84:87], v[32:47]
	s_and_saveexec_b64 s[6:7], vcc
	v_add_f32_e32 v0, v0, v3
	ds_write_b32 v232, v0 offset:49280
	s_or_b64 exec, exec, s[6:7]
	s_waitcnt lgkmcnt(0)
	ds_read_b128 v[4:7], v2 offset:49280
	ds_read_b128 v[8:11], v2 offset:49312
	s_lshl_b32 s2, s2, 12
	s_add_i32 s2, s2, 0
	v_lshlrev_b32_e32 v66, 9, v227
	s_waitcnt lgkmcnt(1)
	v_rcp_f32_e32 v0, v4
	v_rcp_f32_e32 v3, v5
	v_rcp_f32_e32 v12, v6
	v_rcp_f32_e32 v13, v7
	s_waitcnt lgkmcnt(0)
	v_rcp_f32_e32 v14, v8
	ds_read_b128 v[4:7], v2 offset:49344
	v_rcp_f32_e32 v15, v9
	v_rcp_f32_e32 v64, v10
	v_rcp_f32_e32 v65, v11
	ds_read_b128 v[8:11], v2 offset:49376
	s_waitcnt lgkmcnt(1)
	v_rcp_f32_e32 v2, v4
	v_rcp_f32_e32 v4, v5
	v_rcp_f32_e32 v5, v6
	v_rcp_f32_e32 v6, v7
	s_waitcnt lgkmcnt(0)
	v_rcp_f32_e32 v7, v8
	v_rcp_f32_e32 v8, v9
	v_rcp_f32_e32 v9, v10
	v_rcp_f32_e32 v10, v11
	v_lshlrev_b32_e32 v11, 1, v226
	v_mul_f32_e32 v48, v48, v0
	v_mul_f32_e32 v0, v32, v0
	v_add3_u32 v11, s2, v11, v66
	v_cvt_pk_bf16_f32 v0, v0, s0
	ds_write_b16 v11, v0 offset:51264
	v_mul_f32_e32 v0, v49, v3
	v_cvt_pk_bf16_f32 v0, v0, s0
	ds_write_b16 v11, v0 offset:51328
	v_mul_f32_e32 v0, v33, v3
	v_cvt_pk_bf16_f32 v0, v0, s0
	ds_write_b16 v11, v0 offset:51392
	v_mul_f32_e32 v0, v50, v12
	v_cvt_pk_bf16_f32 v0, v0, s0
	ds_write_b16 v11, v0 offset:51456
	v_mul_f32_e32 v0, v34, v12
	v_cvt_pk_bf16_f32 v0, v0, s0
	ds_write_b16 v11, v0 offset:51520
	v_mul_f32_e32 v0, v51, v13
	v_cvt_pk_bf16_f32 v0, v0, s0
	ds_write_b16 v11, v0 offset:51584
	v_mul_f32_e32 v0, v35, v13
	v_cvt_pk_bf16_f32 v0, v0, s0
	ds_write_b16 v11, v0 offset:51648
	v_mul_f32_e32 v0, v52, v14
	v_cvt_pk_bf16_f32 v0, v0, s0
	ds_write_b16 v11, v0 offset:52224
	v_mul_f32_e32 v0, v36, v14
	v_cvt_pk_bf16_f32 v0, v0, s0
	ds_write_b16 v11, v0 offset:52288
	v_mul_f32_e32 v0, v53, v15
	v_cvt_pk_bf16_f32 v0, v0, s0
	ds_write_b16 v11, v0 offset:52352
	v_mul_f32_e32 v0, v37, v15
	v_cvt_pk_bf16_f32 v0, v0, s0
	ds_write_b16 v11, v0 offset:52416
	v_mul_f32_e32 v0, v54, v64
	v_cvt_pk_bf16_f32 v0, v0, s0
	ds_write_b16 v11, v0 offset:52480
	v_mul_f32_e32 v0, v38, v64
	v_cvt_pk_bf16_f32 v0, v0, s0
	ds_write_b16 v11, v0 offset:52544
	v_mul_f32_e32 v0, v55, v65
	v_cvt_pk_bf16_f32 v0, v0, s0
	ds_write_b16 v11, v0 offset:52608
	v_mul_f32_e32 v0, v39, v65
	v_cvt_pk_bf16_f32 v0, v0, s0
	ds_write_b16 v11, v0 offset:52672
	v_mul_f32_e32 v0, v56, v2
	v_cvt_pk_bf16_f32 v0, v0, s0
	ds_write_b16 v11, v0 offset:53248
	v_mul_f32_e32 v0, v40, v2
	v_cvt_pk_bf16_f32 v0, v0, s0
	ds_write_b16 v11, v0 offset:53312
	v_mul_f32_e32 v0, v57, v4
	v_cvt_pk_bf16_f32 v0, v0, s0
	ds_write_b16 v11, v0 offset:53376
	v_mul_f32_e32 v0, v41, v4
	v_cvt_pk_bf16_f32 v0, v0, s0
	ds_write_b16 v11, v0 offset:53440
	v_mul_f32_e32 v0, v58, v5
	v_cvt_pk_bf16_f32 v0, v0, s0
	ds_write_b16 v11, v0 offset:53504
	v_mul_f32_e32 v0, v42, v5
	v_cvt_pk_bf16_f32 v0, v0, s0
	ds_write_b16 v11, v0 offset:53568
	v_mul_f32_e32 v0, v59, v6
	v_cvt_pk_bf16_f32 v0, v0, s0
	ds_write_b16 v11, v0 offset:53632
	v_mul_f32_e32 v0, v43, v6
	v_cvt_pk_bf16_f32 v0, v0, s0
	ds_write_b16 v11, v0 offset:53696
	v_mul_f32_e32 v0, v60, v7
	v_cvt_pk_bf16_f32 v0, v0, s0
	ds_write_b16 v11, v0 offset:54272
	v_mul_f32_e32 v0, v44, v7
	v_cvt_pk_bf16_f32 v0, v0, s0
	ds_write_b16 v11, v0 offset:54336
	v_mul_f32_e32 v0, v61, v8
	v_cvt_pk_bf16_f32 v0, v0, s0
	ds_write_b16 v11, v0 offset:54400
	v_mul_f32_e32 v0, v45, v8
	v_cvt_pk_bf16_f32 v0, v0, s0
	ds_write_b16 v11, v0 offset:54464
	v_mul_f32_e32 v0, v62, v9
	v_cvt_pk_bf16_f32 v0, v0, s0
	ds_write_b16 v11, v0 offset:54528
	v_mul_f32_e32 v0, v46, v9
	v_cvt_pk_bf16_f32 v0, v0, s0
	ds_write_b16 v11, v0 offset:54592
	v_mul_f32_e32 v0, v63, v10
	v_cvt_pk_bf16_f32 v0, v0, s0
	s_lshl_b64 s[4:5], s[4:5], 11
	ds_write_b16 v11, v0 offset:54656
	v_mul_f32_e32 v0, v47, v10
	v_cvt_pk_bf16_f32 v0, v0, s0
	s_add_u32 s4, s38, s4
	ds_write_b16 v11, v0 offset:54720
	s_addc_u32 s5, s39, s5
	s_lshl_b32 s6, s49, 7
	v_lshlrev_b32_e32 v0, 1, v225
	v_cvt_pk_bf16_f32 v48, v48, s0
	s_add_u32 s4, s4, s6
	v_and_b32_e32 v0, 0x70, v0
	ds_write_b16 v11, v48 offset:51200
	s_addc_u32 s5, s5, 0
	v_lshrrev_b32_e32 v14, 3, v224
	v_add_u32_e32 v15, s2, v0
	s_waitcnt lgkmcnt(0)
	v_lshl_add_u64 v[10:11], s[4:5], 0, v[0:1]
	v_lshl_add_u32 v0, v14, 7, v15
	v_or_b32_e32 v32, 8, v14
	ds_read_b128 v[2:5], v0 offset:51200
	v_lshl_add_u32 v6, v32, 7, v15
	ds_read_b128 v[6:9], v6 offset:51200
	v_lshlrev_b32_e32 v0, 11, v14
	v_lshl_add_u64 v[12:13], v[10:11], 0, v[0:1]
	v_lshlrev_b32_e32 v0, 11, v32
	s_waitcnt lgkmcnt(1)
	global_store_dwordx4 v[12:13], v[2:5], off
	s_nop 1
	v_lshl_add_u64 v[2:3], v[10:11], 0, v[0:1]
	v_or_b32_e32 v0, 16, v14
	s_waitcnt lgkmcnt(0)
	global_store_dwordx4 v[2:3], v[6:9], off
	v_lshl_add_u32 v2, v0, 7, v15
	v_or_b32_e32 v14, 24, v14
	ds_read_b128 v[2:5], v2 offset:51200
	v_lshl_add_u32 v6, v14, 7, v15
	ds_read_b128 v[6:9], v6 offset:51200
	v_lshlrev_b32_e32 v0, 11, v0
	v_lshl_add_u64 v[12:13], v[10:11], 0, v[0:1]
	v_lshlrev_b32_e32 v0, 11, v14
	s_waitcnt lgkmcnt(1)
	global_store_dwordx4 v[12:13], v[2:5], off
	s_nop 1
	v_lshl_add_u64 v[2:3], v[10:11], 0, v[0:1]
	s_waitcnt lgkmcnt(0)
	global_store_dwordx4 v[2:3], v[6:9], off
	s_waitcnt lgkmcnt(0)
	s_barrier
	s_and_saveexec_b64 s[4:5], s[0:1]
	s_cbranch_execz .LBB0_770
	s_waitcnt vmcnt(4)
	v_mov_b32_e32 v223, v252
	v_cmp_lt_u32_e32 vcc, s43, v223
	s_and_saveexec_b64 s[6:7], vcc
	s_xor_b64 s[6:7], exec, s[6:7]
	s_cbranch_execz .LBB0_837
	s_add_i32 s8, s44, 1
	s_lshl_b32 s2, s8, 8
	s_and_b32 s2, s2, 0x700
	s_add_i32 s30, s44, 2
	v_mov_b32_e32 v0, s2
	s_lshl_b32 s2, s30, 8
	s_and_b32 s2, s2, 0x700
	s_add_i32 s29, s44, 3
	global_load_dword v5, v0, s[82:83] sc1
	v_mov_b32_e32 v0, s2
	s_lshl_b32 s2, s29, 8
	s_and_b32 s2, s2, 0x700
	s_add_i32 s28, s44, 4
	global_load_dword v7, v0, s[82:83] sc1
	v_mov_b32_e32 v0, s2
	s_lshl_b32 s2, s28, 8
	s_and_b32 s2, s2, 0x700
	s_add_i32 s10, s44, 5
	global_load_dword v6, v0, s[82:83] sc1
	v_mov_b32_e32 v0, s2
	s_lshl_b32 s2, s10, 8
	s_and_b32 s2, s2, 0x700
	global_load_dword v4, v0, s[82:83] sc1
	v_mov_b32_e32 v0, s2
	s_add_i32 s2, s44, 6
	s_lshl_b32 s9, s2, 8
	s_and_b32 s9, s9, 0x700
	s_add_i32 s44, s44, 7
	global_load_dword v3, v0, s[82:83] sc1
	v_mov_b32_e32 v0, s9
	s_lshl_b32 s9, s44, 8
	s_and_b32 s9, s9, 0x700
	global_load_dword v2, v0, s[82:83] sc1
	v_mov_b32_e32 v0, s9
	global_load_dword v0, v0, s[82:83] sc1
	s_waitcnt vmcnt(6)
	v_cmp_gt_u32_e32 vcc, s41, v5
	v_mov_b32_e32 v5, -1
	s_cbranch_vccz .LBB0_806
	s_mov_b64 s[24:25], exec
	v_mbcnt_lo_u32_b32 v5, s24, 0
	v_mbcnt_hi_u32_b32 v5, s25, v5
	s_and_b32 s26, s8, 7
	v_cmp_eq_u32_e32 vcc, 0, v5
	s_and_saveexec_b64 s[8:9], vcc
	s_cbranch_execz .LBB0_805
	s_lshl_b32 s27, s26, 8
	s_bcnt1_i32_b64 s24, s[24:25]
	v_mov_b32_e32 v8, s27
	v_mov_b32_e32 v9, s24
	global_atomic_add v8, v8, v9, s[82:83] sc0

	.amdhsa_kernel _Z6mk_fwd4Args
		.amdhsa_group_segment_fixed_size 0
		.amdhsa_private_segment_fixed_size 0
		.amdhsa_kernarg_size 440
		.amdhsa_user_sgpr_count 2
		.amdhsa_user_sgpr_dispatch_ptr 0
		.amdhsa_user_sgpr_queue_ptr 0
		.amdhsa_user_sgpr_kernarg_segment_ptr 1
		.amdhsa_user_sgpr_dispatch_id 0
		.amdhsa_user_sgpr_kernarg_preload_length 0
		.amdhsa_user_sgpr_kernarg_preload_offset 0
		.amdhsa_user_sgpr_private_segment_size 0
		.amdhsa_uses_dynamic_stack 0
		.amdhsa_enable_private_segment 0
		.amdhsa_system_sgpr_workgroup_id_x 1
		.amdhsa_system_sgpr_workgroup_id_y 0
		.amdhsa_system_sgpr_workgroup_id_z 0
		.amdhsa_system_sgpr_workgroup_info 0
		.amdhsa_system_vgpr_workitem_id 2
		.amdhsa_next_free_vgpr 256
		.amdhsa_next_free_sgpr 102
		.amdhsa_accum_offset 256
		.amdhsa_reserve_vcc 1
		.amdhsa_float_round_mode_32 0
		.amdhsa_float_round_mode_16_64 0
		.amdhsa_float_denorm_mode_32 3
		.amdhsa_float_denorm_mode_16_64 3
		.amdhsa_dx10_clamp 1
		.amdhsa_ieee_mode 1
		.amdhsa_fp16_overflow 0
		.amdhsa_tg_split 0
		.amdhsa_exception_fp_ieee_invalid_op 0
		.amdhsa_exception_fp_denorm_src 0
		.amdhsa_exception_fp_ieee_div_zero 0
		.amdhsa_exception_fp_ieee_overflow 0
		.amdhsa_exception_fp_ieee_underflow 0
		.amdhsa_exception_fp_ieee_inexact 0
		.amdhsa_exception_int_div_zero 0
	.end_amdhsa_kernel

amdhsa.kernels:
  - .agpr_count:     0
    .args:
      - .offset:         0
        .size:           184
        .value_kind:     by_value
      - .offset:         184
        .size:           4
        .value_kind:     hidden_block_count_x
      - .offset:         188
        .size:           4
        .value_kind:     hidden_block_count_y
      - .offset:         192
        .size:           4
        .value_kind:     hidden_block_count_z
      - .offset:         196
        .size:           2
        .value_kind:     hidden_group_size_x
      - .offset:         198
        .size:           2
        .value_kind:     hidden_group_size_y
      - .offset:         200
        .size:           2
        .value_kind:     hidden_group_size_z
      - .offset:         202
        .size:           2
        .value_kind:     hidden_remainder_x
      - .offset:         204
        .size:           2
        .value_kind:     hidden_remainder_y
      - .offset:         206
        .size:           2
        .value_kind:     hidden_remainder_z
      - .offset:         224
        .size:           8
        .value_kind:     hidden_global_offset_x
      - .offset:         232
        .size:           8
        .value_kind:     hidden_global_offset_y
      - .offset:         240
        .size:           8
        .value_kind:     hidden_global_offset_z
      - .offset:         248
        .size:           2
        .value_kind:     hidden_grid_dims
      - .offset:         272
        .size:           8
        .value_kind:     hidden_multigrid_sync_arg
      - .offset:         304
        .size:           4
        .value_kind:     hidden_dynamic_lds_size
    .group_segment_fixed_size: 0
    .kernarg_segment_align: 8
    .kernarg_segment_size: 440
    .language:       OpenCL C
    .language_version:
      - 2
      - 0
    .max_flat_workgroup_size: 512
    .name:           _Z6mk_fwd4Args
    .private_segment_fixed_size: 0
    .sgpr_count:     108
    .sgpr_spill_count: 88
    .symbol:         _Z6mk_fwd4Args.kd
    .uniform_work_group_size: 1
    .uses_dynamic_stack: false
    .vgpr_count:     256
    .vgpr_spill_count: 0
    .wavefront_size: 64
